# mlstm_out Q*C stage: all 16 state fragments loaded right after the preceding barrier, loop unrolled
# baseline (speedup 1.0000x reference)
; __device__ __forceinline__ f32x4 mfma16(bf16x8 a, bf16x8 b, f32x4 c) { return __builtin_amdgcn_mfma_f32_16x16x32_bf16(a, b, c, 0, 0, 0); }
; __device__ __forceinline__ void mlstm_out(const Params& P, unsigned char* shm, int bh, int j) {
;     ...
;     { bf16_t* dst = Qs + (tid >> 5) * 264 + (tid & 31) * 8;
; #pragma unroll
;       for (int i = 0; i < 8; ++i) *(u32x4*)(dst + i * 16 * 264) = qreg[i]; }
;     __syncthreads();
;     {
;         const int wr2 = wave >> 2, wc4 = wave & 3;
;         f32x4 acc[4][2];
; #pragma unroll
;         for (int m = 0; m < 4; ++m) { acc[m][0] = (f32x4){0.f, 0.f, 0.f, 0.f}; acc[m][1] = (f32x4){0.f, 0.f, 0.f, 0.f}; }
;         const bf16_t* qbase = Qs + (64 * wr2 + l16) * 264 + 8 * q;
; #pragma unroll
;         for (int ks = 0; ks < 8; ++ks) {
; #pragma unroll
;             for (int m = 0; m < 4; ++m) { const bf16x8 a = *(const bf16x8*)(qbase + 16 * m * 264 + 32 * ks);
;                 acc[m][0] = mfma16(a, kf[0][ks], acc[m][0]); acc[m][1] = mfma16(a, kf[1][ks], acc[m][1]); } }
.LBB0_554:
	s_or_b64 exec, exec, s[4:5]
	s_waitcnt vmcnt(23)
	ds_write_b128 v136, v[56:59]
	s_waitcnt vmcnt(22)
	ds_write_b128 v136, v[60:63] offset:8448
	s_waitcnt vmcnt(21)
	ds_write_b128 v136, v[64:67] offset:16896
	s_waitcnt vmcnt(20)
	ds_write_b128 v136, v[68:71] offset:25344
	s_waitcnt vmcnt(19)
	ds_write_b128 v136, v[72:75] offset:33792
	s_waitcnt vmcnt(18)
	ds_write_b128 v136, v[76:79] offset:42240
	s_waitcnt vmcnt(17)
	ds_write_b128 v136, v[80:83] offset:50688
	s_waitcnt vmcnt(16)
	ds_write_b128 v136, v[84:87] offset:59136
	s_waitcnt lgkmcnt(0)
	s_barrier
	ds_read_b128 v[56:59], v137
	ds_read_b128 v[64:67], v137 offset:8448
	ds_read_b128 v[72:75], v137 offset:16896
	ds_read_b128 v[80:83], v137 offset:25344
	s_waitcnt vmcnt(3) lgkmcnt(3)
	v_mfma_f32_16x16x32_bf16 v[60:63], v[56:59], v[92:95], 0
	v_mfma_f32_16x16x32_bf16 v[56:59], v[56:59], v[88:91], 0
	s_waitcnt lgkmcnt(2)
	v_mfma_f32_16x16x32_bf16 v[68:71], v[64:67], v[92:95], 0
	v_mfma_f32_16x16x32_bf16 v[64:67], v[64:67], v[88:91], 0
	s_waitcnt lgkmcnt(1)
	v_mfma_f32_16x16x32_bf16 v[76:79], v[72:75], v[92:95], 0
	v_mfma_f32_16x16x32_bf16 v[72:75], v[72:75], v[88:91], 0
	s_waitcnt lgkmcnt(0)
	v_mfma_f32_16x16x32_bf16 v[84:87], v[80:83], v[92:95], 0
	v_mfma_f32_16x16x32_bf16 v[80:83], v[80:83], v[88:91], 0
	ds_read_b128 v[88:91], v137 offset:64
	s_waitcnt lgkmcnt(0)
	v_mfma_f32_16x16x32_bf16 v[60:63], v[88:91], v[52:55], v[60:63]
	v_mfma_f32_16x16x32_bf16 v[56:59], v[88:91], v[48:51], v[56:59]
	ds_read_b128 v[88:91], v137 offset:8512
	s_waitcnt lgkmcnt(0)
	v_mfma_f32_16x16x32_bf16 v[68:71], v[88:91], v[52:55], v[68:71]
	v_mfma_f32_16x16x32_bf16 v[64:67], v[88:91], v[48:51], v[64:67]
	ds_read_b128 v[88:91], v137 offset:16960
	s_waitcnt lgkmcnt(0)
	v_mfma_f32_16x16x32_bf16 v[76:79], v[88:91], v[52:55], v[76:79]
	v_mfma_f32_16x16x32_bf16 v[72:75], v[88:91], v[48:51], v[72:75]
	ds_read_b128 v[88:91], v137 offset:25408
	s_waitcnt lgkmcnt(0)
	v_mfma_f32_16x16x32_bf16 v[48:51], v[88:91], v[48:51], v[80:83]
	s_nop 2
	ds_read_b128 v[80:83], v137 offset:128
	s_waitcnt lgkmcnt(0)
	v_mfma_f32_16x16x32_bf16 v[60:63], v[80:83], v[40:43], v[60:63]
	v_mfma_f32_16x16x32_bf16 v[56:59], v[80:83], v[44:47], v[56:59]
	ds_read_b128 v[80:83], v137 offset:8576
	s_waitcnt lgkmcnt(0)
	v_mfma_f32_16x16x32_bf16 v[68:71], v[80:83], v[40:43], v[68:71]
	v_mfma_f32_16x16x32_bf16 v[64:67], v[80:83], v[44:47], v[64:67]
	ds_read_b128 v[80:83], v137 offset:17024
	s_waitcnt lgkmcnt(0)
	v_mfma_f32_16x16x32_bf16 v[76:79], v[80:83], v[40:43], v[76:79]
	v_mfma_f32_16x16x32_bf16 v[72:75], v[80:83], v[44:47], v[72:75]
	ds_read_b128 v[80:83], v137 offset:25472
	s_waitcnt lgkmcnt(0)
	v_mfma_f32_16x16x32_bf16 v[44:47], v[80:83], v[44:47], v[48:51]
	s_nop 2
	ds_read_b128 v[48:51], v137 offset:192
	v_mfma_f32_16x16x32_bf16 v[52:55], v[88:91], v[52:55], v[84:87]
	v_mfma_f32_16x16x32_bf16 v[40:43], v[80:83], v[40:43], v[52:55]
	s_waitcnt lgkmcnt(0)
	v_mfma_f32_16x16x32_bf16 v[52:55], v[48:51], v[36:39], v[60:63]
	v_mfma_f32_16x16x32_bf16 v[48:51], v[48:51], v[32:35], v[56:59]
	s_nop 2
	ds_read_b128 v[56:59], v137 offset:8640
	s_waitcnt lgkmcnt(0)
	v_mfma_f32_16x16x32_bf16 v[60:63], v[56:59], v[36:39], v[68:71]
	v_mfma_f32_16x16x32_bf16 v[56:59], v[56:59], v[32:35], v[64:67]
	s_nop 2
	ds_read_b128 v[64:67], v137 offset:17088
	s_waitcnt lgkmcnt(0)
	v_mfma_f32_16x16x32_bf16 v[68:71], v[64:67], v[36:39], v[76:79]
	v_mfma_f32_16x16x32_bf16 v[64:67], v[64:67], v[32:35], v[72:75]
	s_nop 2
	ds_read_b128 v[72:75], v137 offset:25536
	s_waitcnt lgkmcnt(0)
	v_mfma_f32_16x16x32_bf16 v[36:39], v[72:75], v[36:39], v[40:43]
	s_nop 2
	ds_read_b128 v[40:43], v137 offset:256
	v_mfma_f32_16x16x32_bf16 v[32:35], v[72:75], v[32:35], v[44:47]
	s_waitcnt lgkmcnt(0)
	v_mfma_f32_16x16x32_bf16 v[44:47], v[40:43], v[24:27], v[52:55]
	v_mfma_f32_16x16x32_bf16 v[40:43], v[40:43], v[28:31], v[48:51]
	s_nop 2
	ds_read_b128 v[48:51], v137 offset:8704
	s_waitcnt lgkmcnt(0)
	v_mfma_f32_16x16x32_bf16 v[52:55], v[48:51], v[24:27], v[60:63]
	v_mfma_f32_16x16x32_bf16 v[48:51], v[48:51], v[28:31], v[56:59]
	s_nop 2
	ds_read_b128 v[56:59], v137 offset:17152
	s_waitcnt lgkmcnt(0)
	v_mfma_f32_16x16x32_bf16 v[60:63], v[56:59], v[24:27], v[68:71]
	v_mfma_f32_16x16x32_bf16 v[56:59], v[56:59], v[28:31], v[64:67]
	s_nop 2
	ds_read_b128 v[64:67], v137 offset:25600
	s_waitcnt lgkmcnt(0)
	v_mfma_f32_16x16x32_bf16 v[28:31], v[64:67], v[28:31], v[32:35]
	s_nop 2
	ds_read_b128 v[32:35], v137 offset:320
	v_mfma_f32_16x16x32_bf16 v[24:27], v[64:67], v[24:27], v[36:39]
	s_waitcnt lgkmcnt(0)
	v_mfma_f32_16x16x32_bf16 v[36:39], v[32:35], v[20:23], v[44:47]
	v_mfma_f32_16x16x32_bf16 v[32:35], v[32:35], v[16:19], v[40:43]
	s_nop 2
	ds_read_b128 v[40:43], v137 offset:8768
	s_waitcnt lgkmcnt(0)
	v_mfma_f32_16x16x32_bf16 v[44:47], v[40:43], v[20:23], v[52:55]
	v_mfma_f32_16x16x32_bf16 v[40:43], v[40:43], v[16:19], v[48:51]
	s_nop 2
	ds_read_b128 v[48:51], v137 offset:17216
	s_waitcnt lgkmcnt(0)
	v_mfma_f32_16x16x32_bf16 v[52:55], v[48:51], v[20:23], v[60:63]
	v_mfma_f32_16x16x32_bf16 v[48:51], v[48:51], v[16:19], v[56:59]
	s_nop 2
	ds_read_b128 v[56:59], v137 offset:25664
	s_waitcnt lgkmcnt(0)
	v_mfma_f32_16x16x32_bf16 v[20:23], v[56:59], v[20:23], v[24:27]
	s_nop 2
	ds_read_b128 v[24:27], v137 offset:384
	v_mfma_f32_16x16x32_bf16 v[16:19], v[56:59], v[16:19], v[28:31]
	s_waitcnt lgkmcnt(0)
	v_mfma_f32_16x16x32_bf16 v[28:31], v[24:27], v[8:11], v[36:39]
	s_waitcnt vmcnt(1)
	v_mfma_f32_16x16x32_bf16 v[32:35], v[24:27], v[12:15], v[32:35]
	ds_read_b128 v[24:27], v137 offset:8832
	s_waitcnt lgkmcnt(0)
; __device__ __forceinline__ bf16_t f2bf(float f) { unsigned u = __float_as_uint(f); u += 0x7FFFu + ((u >> 16) & 1u); return (bf16_t)(u >> 16); }
; __device__ __forceinline__ float bf2f(bf16_t b) { return __uint_as_float(((unsigned)b) << 16); }
; __device__ __forceinline__ float row16_sum(float x) { x += dpp_mov<0x128>(x); x += dpp_mov<0x124>(x); x += dpp_mov<0x122>(x); x += dpp_mov<0x121>(x); return x; }
; __device__ __forceinline__ f32x4 mfma16(bf16x8 a, bf16x8 b, f32x4 c) { return __builtin_amdgcn_mfma_f32_16x16x32_bf16(a, b, c, 0, 0, 0); }
; #define MFMA_SETTLE() do { __builtin_amdgcn_sched_barrier(0); asm volatile("s_nop 15\n\ts_nop 15" ::: "memory"); __builtin_amdgcn_sched_barrier(0); } while (0)
; __device__ __forceinline__ void mlstm_out(const Params& P, unsigned char* shm, int bh, int j) {
;     ...
;                 acc[m][0] = mfma16(a, kf[0][ks], acc[m][0]); acc[m][1] = mfma16(a, kf[1][ks], acc[m][1]); } }
;         MFMA_SETTLE();
;         const int tb = 64 * wr2 + 4 * q, sb = 32 * wc4 + l16;
;         const float as0 = sm[sb], as1 = sm[sb + 16];
;         const float* pMt = sMt + tb; bf16_t* pSs = Ss + tb * 136 + sb; float* pRow = sRow + wc4 * 128 + tb;
; #pragma unroll
;         for (int m = 0; m < 4; ++m)
; #pragma unroll
;             for (int r = 0; r < 4; ++r) { const int t = tb + 16 * m + r; const float Mt = pMt[16 * m + r];
;                 float v0 = 0.f, v1 = 0.f; if (sb <= t) v0 = acc[m][0][r] * 0.0625f * __expf(as0 - Mt); if (sb + 16 <= t) v1 = acc[m][1][r] * 0.0625f * __expf(as1 - Mt);
;                 const bf16_t b0 = f2bf(v0), b1 = f2bf(v1); pSs[(16 * m + r) * 136] = b0; pSs[(16 * m + r) * 136 + 16] = b1;
;                 float rs = bf2f(b0) + bf2f(b1);
;                 rs = row16_sum(rs);
;                 if (l16 == 0) pRow[16 * m + r] = rs; }
	v_mfma_f32_16x16x32_bf16 v[36:39], v[24:27], v[8:11], v[44:47]
	v_mfma_f32_16x16x32_bf16 v[40:43], v[24:27], v[12:15], v[40:43]
	ds_read_b128 v[24:27], v137 offset:17280
	s_waitcnt lgkmcnt(0)
	v_mfma_f32_16x16x32_bf16 v[44:47], v[24:27], v[8:11], v[52:55]
	v_mfma_f32_16x16x32_bf16 v[48:51], v[24:27], v[12:15], v[48:51]
	ds_read_b128 v[24:27], v137 offset:25728
	s_waitcnt lgkmcnt(0)
	v_mfma_f32_16x16x32_bf16 v[52:55], v[24:27], v[8:11], v[20:23]
	ds_read_b128 v[8:11], v137 offset:448
	v_mfma_f32_16x16x32_bf16 v[56:59], v[24:27], v[12:15], v[16:19]
	ds_read_b128 v[12:15], v137 offset:17344
	s_waitcnt lgkmcnt(1)
	v_mfma_f32_16x16x32_bf16 v[24:27], v[8:11], v[0:3], v[28:31]
	s_waitcnt vmcnt(0)
	v_mfma_f32_16x16x32_bf16 v[28:31], v[8:11], v[4:7], v[32:35]
	ds_read_b128 v[8:11], v137 offset:8896
	s_nop 1
	ds_read_b128 v[32:35], v137 offset:25792
	s_waitcnt lgkmcnt(1)
	v_mfma_f32_16x16x32_bf16 v[16:19], v[8:11], v[0:3], v[36:39]
	v_mfma_f32_16x16x32_bf16 v[20:23], v[8:11], v[4:7], v[40:43]
	v_mfma_f32_16x16x32_bf16 v[8:11], v[12:15], v[0:3], v[44:47]
	v_mfma_f32_16x16x32_bf16 v[12:15], v[12:15], v[4:7], v[48:51]
	s_waitcnt lgkmcnt(0)
	v_mfma_f32_16x16x32_bf16 v[0:3], v[32:35], v[0:3], v[52:55]
	v_mfma_f32_16x16x32_bf16 v[4:7], v[32:35], v[4:7], v[56:59]
	s_nop 15
	s_nop 15
	ds_read_b32 v33, v139
	ds_read_b32 v34, v141
	ds_read_b32 v32, v140
	v_mul_f32_e32 v24, 0x3d800000, v24
	v_mul_f32_e32 v28, 0x3d800000, v28
	v_readlane_b32 s4, v244, 14
	s_waitcnt lgkmcnt(1)
	v_sub_f32_e32 v35, v33, v34
	s_waitcnt lgkmcnt(0)
	v_sub_f32_e32 v34, v32, v34
	v_mul_f32_e32 v35, 0x3fb8aa3b, v35
	v_exp_f32_e32 v35, v35
	v_mul_f32_e32 v34, 0x3fb8aa3b, v34
	v_exp_f32_e32 v34, v34
	v_readlane_b32 s5, v244, 15
	v_mul_f32_e32 v24, v24, v35
	v_cndmask_b32_e64 v24, v24, 0, s[28:29]
	v_mul_f32_e32 v28, v28, v34
	v_cndmask_b32_e64 v28, v28, 0, s[4:5]
	v_bfe_u32 v34, v24, 16, 1
	v_add3_u32 v24, v24, v34, s7
	v_bfe_u32 v34, v28, 16, 1
	v_add3_u32 v28, v28, v34, s7
	ds_write_b16_d16_hi v142, v24
	ds_write_b16_d16_hi v142, v28 offset:32
	v_and_b32_e32 v24, 0xffff0000, v24
	v_and_b32_e32 v28, 0xffff0000, v28
	v_add_f32_e32 v24, v24, v28
	v_mov_b32_e32 v28, 0
	s_nop 0
	v_add_f32_dpp v24, v24, v24 row_ror:8 row_mask:0xf bank_mask:0xf bound_ctrl:1
	s_nop 1
	v_add_f32_dpp v24, v24, v24 row_ror:4 row_mask:0xf bank_mask:0xf bound_ctrl:1
	s_nop 1
	v_add_f32_dpp v24, v24, v24 row_ror:2 row_mask:0xf bank_mask:0xf bound_ctrl:1
	s_nop 1
	v_mov_b32_dpp v28, v24 row_ror:1 row_mask:0xf bank_mask:0xf
	s_and_saveexec_b64 s[4:5], s[26:27]
	v_add_f32_e32 v24, v24, v28
	ds_write_b32 v143, v24
	s_or_b64 exec, exec, s[4:5]
	ds_read_b32 v24, v141 offset:4
	v_mul_f32_e32 v25, 0x3d800000, v25
	v_readlane_b32 s4, v244, 16
	v_readlane_b32 s5, v244, 17
	v_mul_f32_e32 v29, 0x3d800000, v29
	s_waitcnt lgkmcnt(0)
	v_sub_f32_e32 v28, v33, v24
	v_mul_f32_e32 v28, 0x3fb8aa3b, v28
	v_sub_f32_e32 v24, v32, v24
	v_exp_f32_e32 v28, v28
	v_mul_f32_e32 v24, 0x3fb8aa3b, v24
	v_exp_f32_e32 v24, v24
	v_mul_f32_e32 v25, v25, v28
	v_cndmask_b32_e64 v25, v25, 0, s[4:5]
	v_readlane_b32 s4, v244, 18
	v_mul_f32_e32 v24, v29, v24
	v_readlane_b32 s5, v244, 19
	v_bfe_u32 v28, v25, 16, 1
	v_add3_u32 v25, v25, v28, s7
	v_cndmask_b32_e64 v24, v24, 0, s[4:5]
	v_bfe_u32 v28, v24, 16, 1
	v_add3_u32 v24, v24, v28, s7
	ds_write_b16_d16_hi v142, v25 offset:272
	ds_write_b16_d16_hi v142, v24 offset:304
	v_and_b32_e32 v25, 0xffff0000, v25
	v_and_b32_e32 v24, 0xffff0000, v24
	v_add_f32_e32 v24, v25, v24
	v_mov_b32_e32 v25, 0
	s_nop 0
	v_add_f32_dpp v24, v24, v24 row_ror:8 row_mask:0xf bank_mask:0xf bound_ctrl:1
	s_nop 1
	v_add_f32_dpp v24, v24, v24 row_ror:4 row_mask:0xf bank_mask:0xf bound_ctrl:1
	s_nop 1
	v_add_f32_dpp v24, v24, v24 row_ror:2 row_mask:0xf bank_mask:0xf bound_ctrl:1
	s_nop 1
	v_mov_b32_dpp v25, v24 row_ror:1 row_mask:0xf bank_mask:0xf
	s_and_saveexec_b64 s[4:5], s[26:27]
	v_add_f32_e32 v24, v24, v25
	ds_write_b32 v143, v24 offset:4
	s_or_b64 exec, exec, s[4:5]
	ds_read_b32 v24, v141 offset:8
	v_mul_f32_e32 v26, 0x3d800000, v26
	v_readlane_b32 s4, v244, 20
	v_readlane_b32 s5, v244, 21
	v_mul_f32_e32 v28, 0x3d800000, v30
	s_waitcnt lgkmcnt(0)
	v_sub_f32_e32 v25, v33, v24
	v_mul_f32_e32 v25, 0x3fb8aa3b, v25
	v_sub_f32_e32 v24, v32, v24
	v_exp_f32_e32 v25, v25
	v_mul_f32_e32 v24, 0x3fb8aa3b, v24
	v_exp_f32_e32 v24, v24
	v_mul_f32_e32 v25, v26, v25
	v_cndmask_b32_e64 v25, v25, 0, s[4:5]
	v_readlane_b32 s4, v244, 22
	v_mul_f32_e32 v24, v28, v24
	v_readlane_b32 s5, v244, 23
	v_bfe_u32 v26, v25, 16, 1
	v_add3_u32 v25, v25, v26, s7
	v_cndmask_b32_e64 v24, v24, 0, s[4:5]
	v_bfe_u32 v26, v24, 16, 1
	v_add3_u32 v24, v24, v26, s7
	ds_write_b16_d16_hi v142, v25 offset:544
	ds_write_b16_d16_hi v142, v24 offset:576
	v_and_b32_e32 v25, 0xffff0000, v25
	v_and_b32_e32 v24, 0xffff0000, v24
	v_add_f32_e32 v24, v25, v24
	v_mov_b32_e32 v25, 0
	s_nop 0
	v_add_f32_dpp v24, v24, v24 row_ror:8 row_mask:0xf bank_mask:0xf bound_ctrl:1
	s_nop 1
	v_add_f32_dpp v24, v24, v24 row_ror:4 row_mask:0xf bank_mask:0xf bound_ctrl:1
	s_nop 1
	v_add_f32_dpp v24, v24, v24 row_ror:2 row_mask:0xf bank_mask:0xf bound_ctrl:1
	s_nop 1
	v_mov_b32_dpp v25, v24 row_ror:1 row_mask:0xf bank_mask:0xf
	s_and_saveexec_b64 s[4:5], s[26:27]
	v_add_f32_e32 v24, v24, v25
	ds_write_b32 v143, v24 offset:8
	s_or_b64 exec, exec, s[4:5]
	ds_read_b32 v24, v141 offset:12
	v_mul_f32_e32 v26, 0x3d800000, v27
	v_readlane_b32 s4, v244, 24
	v_readlane_b32 s5, v244, 25
	v_mul_f32_e32 v27, 0x3d800000, v31
	s_waitcnt lgkmcnt(0)
; __device__ __forceinline__ bf16_t f2bf(float f) { unsigned u = __float_as_uint(f); u += 0x7FFFu + ((u >> 16) & 1u); return (bf16_t)(u >> 16); }
; __device__ __forceinline__ float bf2f(bf16_t b) { return __uint_as_float(((unsigned)b) << 16); }
; __device__ __forceinline__ float row16_sum(float x) { x += dpp_mov<0x128>(x); x += dpp_mov<0x124>(x); x += dpp_mov<0x122>(x); x += dpp_mov<0x121>(x); return x; }
; __device__ __forceinline__ void mlstm_out(const Params& P, unsigned char* shm, int bh, int j) {
;     ...
;             for (int r = 0; r < 4; ++r) { const int t = tb + 16 * m + r; const float Mt = pMt[16 * m + r];
;                 float v0 = 0.f, v1 = 0.f; if (sb <= t) v0 = acc[m][0][r] * 0.0625f * __expf(as0 - Mt); if (sb + 16 <= t) v1 = acc[m][1][r] * 0.0625f * __expf(as1 - Mt);
;                 const bf16_t b0 = f2bf(v0), b1 = f2bf(v1); pSs[(16 * m + r) * 136] = b0; pSs[(16 * m + r) * 136 + 16] = b1;
;                 float rs = bf2f(b0) + bf2f(b1);
;                 rs = row16_sum(rs);
;                 if (l16 == 0) pRow[16 * m + r] = rs; }
	v_sub_f32_e32 v25, v33, v24
	v_mul_f32_e32 v25, 0x3fb8aa3b, v25
	v_sub_f32_e32 v24, v32, v24
	v_exp_f32_e32 v25, v25
	v_mul_f32_e32 v24, 0x3fb8aa3b, v24
	v_exp_f32_e32 v24, v24
	v_mul_f32_e32 v25, v26, v25
	v_cndmask_b32_e64 v25, v25, 0, s[4:5]
	v_readlane_b32 s4, v244, 26
	v_mul_f32_e32 v24, v27, v24
	v_readlane_b32 s5, v244, 27
	v_bfe_u32 v26, v25, 16, 1
	v_add3_u32 v25, v25, v26, s7
	v_cndmask_b32_e64 v24, v24, 0, s[4:5]
	v_bfe_u32 v26, v24, 16, 1
	v_add3_u32 v24, v24, v26, s7
	ds_write_b16_d16_hi v142, v25 offset:816
	ds_write_b16_d16_hi v142, v24 offset:848
	v_and_b32_e32 v25, 0xffff0000, v25
	v_and_b32_e32 v24, 0xffff0000, v24
	v_add_f32_e32 v24, v25, v24
	v_mov_b32_e32 v25, 0
	s_nop 0
	v_add_f32_dpp v24, v24, v24 row_ror:8 row_mask:0xf bank_mask:0xf bound_ctrl:1
	s_nop 1
	v_add_f32_dpp v24, v24, v24 row_ror:4 row_mask:0xf bank_mask:0xf bound_ctrl:1
	s_nop 1
	v_add_f32_dpp v24, v24, v24 row_ror:2 row_mask:0xf bank_mask:0xf bound_ctrl:1
	s_nop 1
	v_mov_b32_dpp v25, v24 row_ror:1 row_mask:0xf bank_mask:0xf
	s_and_saveexec_b64 s[4:5], s[26:27]
	v_add_f32_e32 v24, v24, v25
	ds_write_b32 v143, v24 offset:12
	s_or_b64 exec, exec, s[4:5]
	ds_read_b32 v24, v141 offset:64
	v_mul_f32_e32 v16, 0x3d800000, v16
	v_readlane_b32 s4, v244, 28
	v_mul_f32_e32 v20, 0x3d800000, v20
	v_readlane_b32 s5, v244, 29
	s_waitcnt lgkmcnt(0)
	v_sub_f32_e32 v25, v33, v24
	v_sub_f32_e32 v24, v32, v24
	v_mul_f32_e32 v25, 0x3fb8aa3b, v25
	v_mul_f32_e32 v24, 0x3fb8aa3b, v24
	v_exp_f32_e32 v25, v25
	v_exp_f32_e32 v24, v24
	v_mul_f32_e32 v16, v16, v25
	v_mul_f32_e32 v20, v20, v24
	v_cndmask_b32_e64 v16, v16, 0, s[4:5]
	v_cndmask_b32_e64 v20, v20, 0, s[28:29]
	v_bfe_u32 v24, v16, 16, 1
	v_add3_u32 v16, v16, v24, s7
	v_bfe_u32 v24, v20, 16, 1
	v_add3_u32 v20, v20, v24, s7
	ds_write_b16_d16_hi v142, v16 offset:4352
	ds_write_b16_d16_hi v142, v20 offset:4384
	v_and_b32_e32 v16, 0xffff0000, v16
	v_and_b32_e32 v20, 0xffff0000, v20
	v_add_f32_e32 v16, v16, v20
	v_mov_b32_e32 v20, 0
	s_nop 0
	v_add_f32_dpp v16, v16, v16 row_ror:8 row_mask:0xf bank_mask:0xf bound_ctrl:1
	s_nop 1
	v_add_f32_dpp v16, v16, v16 row_ror:4 row_mask:0xf bank_mask:0xf bound_ctrl:1
	s_nop 1
	v_add_f32_dpp v16, v16, v16 row_ror:2 row_mask:0xf bank_mask:0xf bound_ctrl:1
	s_nop 1
	v_mov_b32_dpp v20, v16 row_ror:1 row_mask:0xf bank_mask:0xf
	s_and_saveexec_b64 s[4:5], s[26:27]
	v_add_f32_e32 v16, v16, v20
	ds_write_b32 v143, v16 offset:64
	s_or_b64 exec, exec, s[4:5]
	ds_read_b32 v16, v141 offset:68
	v_mul_f32_e32 v17, 0x3d800000, v17
	v_readlane_b32 s4, v244, 30
	v_readlane_b32 s5, v244, 31
	v_mul_f32_e32 v21, 0x3d800000, v21
	s_waitcnt lgkmcnt(0)
	v_sub_f32_e32 v20, v33, v16
	v_mul_f32_e32 v20, 0x3fb8aa3b, v20
	v_sub_f32_e32 v16, v32, v16
	v_exp_f32_e32 v20, v20
	v_mul_f32_e32 v16, 0x3fb8aa3b, v16
	v_exp_f32_e32 v16, v16
	v_mul_f32_e32 v17, v17, v20
	v_cndmask_b32_e64 v17, v17, 0, s[4:5]
	v_readlane_b32 s4, v244, 32
	v_mul_f32_e32 v16, v21, v16
	v_readlane_b32 s5, v244, 33
	v_bfe_u32 v20, v17, 16, 1
	v_add3_u32 v17, v17, v20, s7
	v_cndmask_b32_e64 v16, v16, 0, s[4:5]
	v_bfe_u32 v20, v16, 16, 1
	v_add3_u32 v16, v16, v20, s7
	ds_write_b16_d16_hi v142, v17 offset:4624
	ds_write_b16_d16_hi v142, v16 offset:4656
	v_and_b32_e32 v17, 0xffff0000, v17
	v_and_b32_e32 v16, 0xffff0000, v16
	v_add_f32_e32 v16, v17, v16
	v_mov_b32_e32 v17, 0
	s_nop 0
	v_add_f32_dpp v16, v16, v16 row_ror:8 row_mask:0xf bank_mask:0xf bound_ctrl:1
	s_nop 1
	v_add_f32_dpp v16, v16, v16 row_ror:4 row_mask:0xf bank_mask:0xf bound_ctrl:1
	s_nop 1
	v_add_f32_dpp v16, v16, v16 row_ror:2 row_mask:0xf bank_mask:0xf bound_ctrl:1
	s_nop 1
	v_mov_b32_dpp v17, v16 row_ror:1 row_mask:0xf bank_mask:0xf
	s_and_saveexec_b64 s[4:5], s[26:27]
	v_add_f32_e32 v16, v16, v17
	ds_write_b32 v143, v16 offset:68
	s_or_b64 exec, exec, s[4:5]
	ds_read_b32 v16, v141 offset:72
	v_mul_f32_e32 v18, 0x3d800000, v18
	v_readlane_b32 s4, v244, 34
	v_readlane_b32 s5, v244, 35
	v_mul_f32_e32 v20, 0x3d800000, v22
	s_waitcnt lgkmcnt(0)
	v_sub_f32_e32 v17, v33, v16
	v_mul_f32_e32 v17, 0x3fb8aa3b, v17
	v_sub_f32_e32 v16, v32, v16
	v_exp_f32_e32 v17, v17
	v_mul_f32_e32 v16, 0x3fb8aa3b, v16
	v_exp_f32_e32 v16, v16
	v_mul_f32_e32 v17, v18, v17
	v_cndmask_b32_e64 v17, v17, 0, s[4:5]
	v_readlane_b32 s4, v244, 36
	v_mul_f32_e32 v16, v20, v16
	v_readlane_b32 s5, v244, 37
	v_bfe_u32 v18, v17, 16, 1
	v_add3_u32 v17, v17, v18, s7
	v_cndmask_b32_e64 v16, v16, 0, s[4:5]
	v_bfe_u32 v18, v16, 16, 1
	v_add3_u32 v16, v16, v18, s7
	ds_write_b16_d16_hi v142, v17 offset:4896
	ds_write_b16_d16_hi v142, v16 offset:4928
	v_and_b32_e32 v17, 0xffff0000, v17
	v_and_b32_e32 v16, 0xffff0000, v16
	v_add_f32_e32 v16, v17, v16
	v_mov_b32_e32 v17, 0
	s_nop 0
	v_add_f32_dpp v16, v16, v16 row_ror:8 row_mask:0xf bank_mask:0xf bound_ctrl:1
	s_nop 1
	v_add_f32_dpp v16, v16, v16 row_ror:4 row_mask:0xf bank_mask:0xf bound_ctrl:1
	s_nop 1
	v_add_f32_dpp v16, v16, v16 row_ror:2 row_mask:0xf bank_mask:0xf bound_ctrl:1
	s_nop 1
	v_mov_b32_dpp v17, v16 row_ror:1 row_mask:0xf bank_mask:0xf
	s_and_saveexec_b64 s[4:5], s[26:27]
	v_add_f32_e32 v16, v16, v17
	ds_write_b32 v143, v16 offset:72
	s_or_b64 exec, exec, s[4:5]
	ds_read_b32 v16, v141 offset:76
	v_mul_f32_e32 v18, 0x3d800000, v19
	v_mul_f32_e32 v19, 0x3d800000, v23
	s_waitcnt lgkmcnt(0)
; __device__ __forceinline__ bf16_t f2bf(float f) { unsigned u = __float_as_uint(f); u += 0x7FFFu + ((u >> 16) & 1u); return (bf16_t)(u >> 16); }
; __device__ __forceinline__ float bf2f(bf16_t b) { return __uint_as_float(((unsigned)b) << 16); }
; __device__ __forceinline__ float row16_sum(float x) { x += dpp_mov<0x128>(x); x += dpp_mov<0x124>(x); x += dpp_mov<0x122>(x); x += dpp_mov<0x121>(x); return x; }
; __device__ __forceinline__ void mlstm_out(const Params& P, unsigned char* shm, int bh, int j) {
;     ...
;             for (int r = 0; r < 4; ++r) { const int t = tb + 16 * m + r; const float Mt = pMt[16 * m + r];
;                 float v0 = 0.f, v1 = 0.f; if (sb <= t) v0 = acc[m][0][r] * 0.0625f * __expf(as0 - Mt); if (sb + 16 <= t) v1 = acc[m][1][r] * 0.0625f * __expf(as1 - Mt);
;                 const bf16_t b0 = f2bf(v0), b1 = f2bf(v1); pSs[(16 * m + r) * 136] = b0; pSs[(16 * m + r) * 136 + 16] = b1;
;                 float rs = bf2f(b0) + bf2f(b1);
;                 rs = row16_sum(rs);
;                 if (l16 == 0) pRow[16 * m + r] = rs; }
	v_sub_f32_e32 v17, v33, v16
	v_sub_f32_e32 v16, v32, v16
	v_mul_f32_e32 v17, 0x3fb8aa3b, v17
	v_mul_f32_e32 v16, 0x3fb8aa3b, v16
	v_exp_f32_e32 v17, v17
	v_exp_f32_e32 v16, v16
	v_mul_f32_e32 v17, v18, v17
	v_mul_f32_e32 v16, v19, v16
	v_cndmask_b32_e64 v17, v17, 0, s[78:79]
	v_cndmask_b32_e64 v16, v16, 0, s[80:81]
	v_bfe_u32 v18, v17, 16, 1
	v_add3_u32 v17, v17, v18, s7
	v_bfe_u32 v18, v16, 16, 1
	v_add3_u32 v16, v16, v18, s7
	ds_write_b16_d16_hi v142, v17 offset:5168
	ds_write_b16_d16_hi v142, v16 offset:5200
	v_and_b32_e32 v17, 0xffff0000, v17
	v_and_b32_e32 v16, 0xffff0000, v16
	v_add_f32_e32 v16, v17, v16
	v_mov_b32_e32 v17, 0
	s_nop 0
	v_add_f32_dpp v16, v16, v16 row_ror:8 row_mask:0xf bank_mask:0xf bound_ctrl:1
	s_nop 1
	v_add_f32_dpp v16, v16, v16 row_ror:4 row_mask:0xf bank_mask:0xf bound_ctrl:1
	s_nop 1
	v_add_f32_dpp v16, v16, v16 row_ror:2 row_mask:0xf bank_mask:0xf bound_ctrl:1
	s_nop 1
	v_mov_b32_dpp v17, v16 row_ror:1 row_mask:0xf bank_mask:0xf
	s_and_saveexec_b64 s[4:5], s[26:27]
	v_add_f32_e32 v16, v16, v17
	ds_write_b32 v143, v16 offset:76
	s_or_b64 exec, exec, s[4:5]
	ds_read_b32 v16, v141 offset:128
	v_mul_f32_e32 v8, 0x3d800000, v8
	v_mul_f32_e32 v12, 0x3d800000, v12
	v_readlane_b32 s4, v244, 38
	v_readlane_b32 s5, v244, 39
	s_waitcnt lgkmcnt(0)
	v_sub_f32_e32 v17, v33, v16
	v_sub_f32_e32 v16, v32, v16
	v_mul_f32_e32 v17, 0x3fb8aa3b, v17
	v_mul_f32_e32 v16, 0x3fb8aa3b, v16
	v_exp_f32_e32 v17, v17
	v_exp_f32_e32 v16, v16
	v_mul_f32_e32 v8, v8, v17
	v_mul_f32_e32 v12, v12, v16
	v_cndmask_b32_e64 v8, v8, 0, s[82:83]
	v_cndmask_b32_e64 v12, v12, 0, s[4:5]
	v_bfe_u32 v16, v8, 16, 1
	v_add3_u32 v8, v8, v16, s7
	v_bfe_u32 v16, v12, 16, 1
	v_add3_u32 v12, v12, v16, s7
	ds_write_b16_d16_hi v142, v8 offset:8704
	ds_write_b16_d16_hi v142, v12 offset:8736
	v_and_b32_e32 v8, 0xffff0000, v8
	v_and_b32_e32 v12, 0xffff0000, v12
	v_add_f32_e32 v8, v8, v12
	v_mov_b32_e32 v12, 0
	s_nop 0
	v_add_f32_dpp v8, v8, v8 row_ror:8 row_mask:0xf bank_mask:0xf bound_ctrl:1
	s_nop 1
	v_add_f32_dpp v8, v8, v8 row_ror:4 row_mask:0xf bank_mask:0xf bound_ctrl:1
	s_nop 1
	v_add_f32_dpp v8, v8, v8 row_ror:2 row_mask:0xf bank_mask:0xf bound_ctrl:1
	s_nop 1
	v_mov_b32_dpp v12, v8 row_ror:1 row_mask:0xf bank_mask:0xf
	s_and_saveexec_b64 s[4:5], s[26:27]
	v_add_f32_e32 v8, v8, v12
	ds_write_b32 v143, v8 offset:128
	s_or_b64 exec, exec, s[4:5]
	ds_read_b32 v8, v141 offset:132
	v_mul_f32_e32 v9, 0x3d800000, v9
	v_readlane_b32 s4, v244, 40
	v_mul_f32_e32 v13, 0x3d800000, v13
	v_readlane_b32 s5, v244, 41
	s_waitcnt lgkmcnt(0)
	v_sub_f32_e32 v12, v33, v8
	v_sub_f32_e32 v8, v32, v8
	v_mul_f32_e32 v12, 0x3fb8aa3b, v12
	v_mul_f32_e32 v8, 0x3fb8aa3b, v8
	v_exp_f32_e32 v12, v12
	v_exp_f32_e32 v8, v8
	v_mul_f32_e32 v9, v9, v12
	v_mul_f32_e32 v8, v13, v8
	v_cndmask_b32_e64 v9, v9, 0, s[4:5]
	v_cndmask_b32_e64 v8, v8, 0, s[40:41]
	v_bfe_u32 v12, v9, 16, 1
	v_add3_u32 v9, v9, v12, s7
	v_bfe_u32 v12, v8, 16, 1
	v_add3_u32 v8, v8, v12, s7
	ds_write_b16_d16_hi v142, v9 offset:8976
	ds_write_b16_d16_hi v142, v8 offset:9008
	v_and_b32_e32 v9, 0xffff0000, v9
	v_and_b32_e32 v8, 0xffff0000, v8
	v_add_f32_e32 v8, v9, v8
	v_mov_b32_e32 v9, 0
	s_nop 0
	v_add_f32_dpp v8, v8, v8 row_ror:8 row_mask:0xf bank_mask:0xf bound_ctrl:1
	s_nop 1
	v_add_f32_dpp v8, v8, v8 row_ror:4 row_mask:0xf bank_mask:0xf bound_ctrl:1
	s_nop 1
	v_add_f32_dpp v8, v8, v8 row_ror:2 row_mask:0xf bank_mask:0xf bound_ctrl:1
	s_nop 1
	v_mov_b32_dpp v9, v8 row_ror:1 row_mask:0xf bank_mask:0xf
	s_and_saveexec_b64 s[4:5], s[26:27]
	v_add_f32_e32 v8, v8, v9
	ds_write_b32 v143, v8 offset:132
	s_or_b64 exec, exec, s[4:5]
	ds_read_b32 v8, v141 offset:136
	v_mul_f32_e32 v10, 0x3d800000, v10
	v_mul_f32_e32 v12, 0x3d800000, v14
	s_waitcnt lgkmcnt(0)
	v_sub_f32_e32 v9, v33, v8
	v_sub_f32_e32 v8, v32, v8
	v_mul_f32_e32 v9, 0x3fb8aa3b, v9
	v_mul_f32_e32 v8, 0x3fb8aa3b, v8
	v_exp_f32_e32 v9, v9
	v_exp_f32_e32 v8, v8
	v_mul_f32_e32 v9, v10, v9
	v_mul_f32_e32 v8, v12, v8
	v_cndmask_b32_e64 v9, v9, 0, s[72:73]
	v_cndmask_b32_e64 v8, v8, 0, s[70:71]
	v_bfe_u32 v10, v9, 16, 1
	v_add3_u32 v9, v9, v10, s7
	v_bfe_u32 v10, v8, 16, 1
	v_add3_u32 v8, v8, v10, s7
	ds_write_b16_d16_hi v142, v9 offset:9248
	ds_write_b16_d16_hi v142, v8 offset:9280
	v_and_b32_e32 v9, 0xffff0000, v9
	v_and_b32_e32 v8, 0xffff0000, v8
	v_add_f32_e32 v8, v9, v8
	v_mov_b32_e32 v9, 0
	s_nop 0
	v_add_f32_dpp v8, v8, v8 row_ror:8 row_mask:0xf bank_mask:0xf bound_ctrl:1
	s_nop 1
	v_add_f32_dpp v8, v8, v8 row_ror:4 row_mask:0xf bank_mask:0xf bound_ctrl:1
	s_nop 1
	v_add_f32_dpp v8, v8, v8 row_ror:2 row_mask:0xf bank_mask:0xf bound_ctrl:1
	s_nop 1
	v_mov_b32_dpp v9, v8 row_ror:1 row_mask:0xf bank_mask:0xf
	s_and_saveexec_b64 s[4:5], s[26:27]
	v_add_f32_e32 v8, v8, v9
	ds_write_b32 v143, v8 offset:136
	s_or_b64 exec, exec, s[4:5]
	ds_read_b32 v8, v141 offset:140
	v_mul_f32_e32 v10, 0x3d800000, v11
	v_mul_f32_e32 v11, 0x3d800000, v15
	s_waitcnt lgkmcnt(0)
	v_sub_f32_e32 v9, v33, v8
	v_sub_f32_e32 v8, v32, v8
	v_mul_f32_e32 v9, 0x3fb8aa3b, v9
	v_mul_f32_e32 v8, 0x3fb8aa3b, v8
	v_exp_f32_e32 v9, v9
	v_exp_f32_e32 v8, v8
	v_mul_f32_e32 v9, v10, v9
	v_mul_f32_e32 v8, v11, v8
	v_cndmask_b32_e64 v9, v9, 0, s[42:43]
	v_cndmask_b32_e64 v8, v8, 0, s[16:17]
	v_bfe_u32 v10, v9, 16, 1
	v_add3_u32 v9, v9, v10, s7
	v_bfe_u32 v10, v8, 16, 1
	v_add3_u32 v8, v8, v10, s7
	ds_write_b16_d16_hi v142, v9 offset:9520
	ds_write_b16_d16_hi v142, v8 offset:9552
	v_and_b32_e32 v9, 0xffff0000, v9
	v_and_b32_e32 v8, 0xffff0000, v8
	v_add_f32_e32 v8, v9, v8
	v_mov_b32_e32 v9, 0
	s_nop 0
	v_add_f32_dpp v8, v8, v8 row_ror:8 row_mask:0xf bank_mask:0xf bound_ctrl:1
	s_nop 1
	v_add_f32_dpp v8, v8, v8 row_ror:4 row_mask:0xf bank_mask:0xf bound_ctrl:1
	s_nop 1
	v_add_f32_dpp v8, v8, v8 row_ror:2 row_mask:0xf bank_mask:0xf bound_ctrl:1
	s_nop 1
	v_mov_b32_dpp v9, v8 row_ror:1 row_mask:0xf bank_mask:0xf
	s_and_saveexec_b64 s[4:5], s[26:27]
	v_add_f32_e32 v8, v8, v9
	ds_write_b32 v143, v8 offset:140
	s_or_b64 exec, exec, s[4:5]
	ds_read_b32 v8, v141 offset:192
	v_mul_f32_e32 v0, 0x3d800000, v0
	v_mul_f32_e32 v4, 0x3d800000, v4
	s_waitcnt lgkmcnt(0)
; __device__ __forceinline__ bf16_t f2bf(float f) { unsigned u = __float_as_uint(f); u += 0x7FFFu + ((u >> 16) & 1u); return (bf16_t)(u >> 16); }
; __device__ __forceinline__ float bf2f(bf16_t b) { return __uint_as_float(((unsigned)b) << 16); }
; __device__ __forceinline__ float row16_sum(float x) { x += dpp_mov<0x128>(x); x += dpp_mov<0x124>(x); x += dpp_mov<0x122>(x); x += dpp_mov<0x121>(x); return x; }
; __device__ __forceinline__ void mlstm_out(const Params& P, unsigned char* shm, int bh, int j) {
;     ...
;             for (int r = 0; r < 4; ++r) { const int t = tb + 16 * m + r; const float Mt = pMt[16 * m + r];
;                 float v0 = 0.f, v1 = 0.f; if (sb <= t) v0 = acc[m][0][r] * 0.0625f * __expf(as0 - Mt); if (sb + 16 <= t) v1 = acc[m][1][r] * 0.0625f * __expf(as1 - Mt);
;                 const bf16_t b0 = f2bf(v0), b1 = f2bf(v1); pSs[(16 * m + r) * 136] = b0; pSs[(16 * m + r) * 136 + 16] = b1;
;                 float rs = bf2f(b0) + bf2f(b1);
;                 rs = row16_sum(rs);
;                 if (l16 == 0) pRow[16 * m + r] = rs; }
;     }
;     __syncthreads();
;     ...
;         const bf16_t* cbase = (const bf16_t*)(P.ws + O_CTB) + (size_t)(bh * 16 + j - 1) * 65536 + (32 * wave + l16) * 256 + 8 * q;
;         const bf16_t* qbase = Qs + l16 * 264 + 8 * q;
; #pragma unroll 2
;         for (int ks = 0; ks < 8; ++ks) { const bf16x8 cf0 = *(const bf16x8*)(cbase + 32 * ks), cf1 = *(const bf16x8*)(cbase + 16 * 256 + 32 * ks);
	v_sub_f32_e32 v9, v33, v8
	v_sub_f32_e32 v8, v32, v8
	v_mul_f32_e32 v9, 0x3fb8aa3b, v9
	v_mul_f32_e32 v8, 0x3fb8aa3b, v8
	v_exp_f32_e32 v9, v9
	v_exp_f32_e32 v8, v8
	v_mul_f32_e32 v0, v0, v9
	v_mul_f32_e32 v4, v4, v8
	v_cndmask_b32_e64 v0, v0, 0, s[20:21]
	v_cndmask_b32_e64 v4, v4, 0, s[30:31]
	v_bfe_u32 v8, v0, 16, 1
	v_add3_u32 v0, v0, v8, s7
	v_bfe_u32 v8, v4, 16, 1
	v_add3_u32 v4, v4, v8, s7
	ds_write_b16_d16_hi v142, v0 offset:13056
	ds_write_b16_d16_hi v142, v4 offset:13088
	v_and_b32_e32 v0, 0xffff0000, v0
	v_and_b32_e32 v4, 0xffff0000, v4
	v_add_f32_e32 v0, v0, v4
	v_mov_b32_e32 v4, 0
	s_nop 0
	v_add_f32_dpp v0, v0, v0 row_ror:8 row_mask:0xf bank_mask:0xf bound_ctrl:1
	s_nop 1
	v_add_f32_dpp v0, v0, v0 row_ror:4 row_mask:0xf bank_mask:0xf bound_ctrl:1
	s_nop 1
	v_add_f32_dpp v0, v0, v0 row_ror:2 row_mask:0xf bank_mask:0xf bound_ctrl:1
	s_nop 1
	v_mov_b32_dpp v4, v0 row_ror:1 row_mask:0xf bank_mask:0xf
	s_and_saveexec_b64 s[4:5], s[26:27]
	v_add_f32_e32 v0, v0, v4
	ds_write_b32 v143, v0 offset:192
	s_or_b64 exec, exec, s[4:5]
	ds_read_b32 v0, v141 offset:196
	v_mul_f32_e32 v1, 0x3d800000, v1
	v_mul_f32_e32 v5, 0x3d800000, v5
	s_waitcnt lgkmcnt(0)
	v_sub_f32_e32 v4, v33, v0
	v_sub_f32_e32 v0, v32, v0
	v_mul_f32_e32 v4, 0x3fb8aa3b, v4
	v_mul_f32_e32 v0, 0x3fb8aa3b, v0
	v_exp_f32_e32 v4, v4
	v_exp_f32_e32 v0, v0
	v_mul_f32_e32 v1, v1, v4
	v_mul_f32_e32 v0, v5, v0
	v_cndmask_b32_e64 v1, v1, 0, s[34:35]
	v_cndmask_b32_e64 v0, v0, 0, s[0:1]
	v_bfe_u32 v4, v1, 16, 1
	v_add3_u32 v1, v1, v4, s7
	v_bfe_u32 v4, v0, 16, 1
	v_add3_u32 v0, v0, v4, s7
	ds_write_b16_d16_hi v142, v1 offset:13328
	ds_write_b16_d16_hi v142, v0 offset:13360
	v_and_b32_e32 v1, 0xffff0000, v1
	v_and_b32_e32 v0, 0xffff0000, v0
	v_add_f32_e32 v0, v1, v0
	v_mov_b32_e32 v1, 0
	s_nop 0
	v_add_f32_dpp v0, v0, v0 row_ror:8 row_mask:0xf bank_mask:0xf bound_ctrl:1
	s_nop 1
	v_add_f32_dpp v0, v0, v0 row_ror:4 row_mask:0xf bank_mask:0xf bound_ctrl:1
	s_nop 1
	v_add_f32_dpp v0, v0, v0 row_ror:2 row_mask:0xf bank_mask:0xf bound_ctrl:1
	s_nop 1
	v_mov_b32_dpp v1, v0 row_ror:1 row_mask:0xf bank_mask:0xf
	s_and_saveexec_b64 s[4:5], s[26:27]
	v_add_f32_e32 v0, v0, v1
	ds_write_b32 v143, v0 offset:196
	s_or_b64 exec, exec, s[4:5]
	ds_read_b32 v0, v141 offset:200
	v_mul_f32_e32 v2, 0x3d800000, v2
	v_mul_f32_e32 v4, 0x3d800000, v6
	s_waitcnt lgkmcnt(0)
	v_sub_f32_e32 v1, v33, v0
	v_sub_f32_e32 v0, v32, v0
	v_mul_f32_e32 v1, 0x3fb8aa3b, v1
	v_mul_f32_e32 v0, 0x3fb8aa3b, v0
	v_exp_f32_e32 v1, v1
	v_exp_f32_e32 v0, v0
	v_mul_f32_e32 v1, v2, v1
	v_mul_f32_e32 v0, v4, v0
	v_cndmask_b32_e64 v1, v1, 0, s[84:85]
	v_cndmask_b32_e64 v0, v0, 0, s[86:87]
	v_bfe_u32 v2, v1, 16, 1
	v_add3_u32 v1, v1, v2, s7
	v_bfe_u32 v2, v0, 16, 1
	v_add3_u32 v0, v0, v2, s7
	ds_write_b16_d16_hi v142, v1 offset:13600
	ds_write_b16_d16_hi v142, v0 offset:13632
	v_and_b32_e32 v1, 0xffff0000, v1
	v_and_b32_e32 v0, 0xffff0000, v0
	v_add_f32_e32 v0, v1, v0
	v_mov_b32_e32 v1, 0
	s_nop 0
	v_add_f32_dpp v0, v0, v0 row_ror:8 row_mask:0xf bank_mask:0xf bound_ctrl:1
	s_nop 1
	v_add_f32_dpp v0, v0, v0 row_ror:4 row_mask:0xf bank_mask:0xf bound_ctrl:1
	s_nop 1
	v_add_f32_dpp v0, v0, v0 row_ror:2 row_mask:0xf bank_mask:0xf bound_ctrl:1
	s_nop 1
	v_mov_b32_dpp v1, v0 row_ror:1 row_mask:0xf bank_mask:0xf
	s_and_saveexec_b64 s[4:5], s[26:27]
	v_add_f32_e32 v0, v0, v1
	ds_write_b32 v143, v0 offset:200
	s_or_b64 exec, exec, s[4:5]
	ds_read_b32 v0, v141 offset:204
	v_mul_f32_e32 v2, 0x3d800000, v3
	v_mul_f32_e32 v3, 0x3d800000, v7
	s_waitcnt lgkmcnt(0)
	v_sub_f32_e32 v1, v33, v0
	v_sub_f32_e32 v0, v32, v0
	v_mul_f32_e32 v1, 0x3fb8aa3b, v1
	v_mul_f32_e32 v0, 0x3fb8aa3b, v0
	v_exp_f32_e32 v1, v1
	v_exp_f32_e32 v0, v0
	v_mul_f32_e32 v1, v2, v1
	v_mul_f32_e32 v0, v3, v0
	v_cndmask_b32_e64 v1, v1, 0, s[88:89]
	v_cndmask_b32_e64 v0, v0, 0, s[90:91]
	v_bfe_u32 v2, v1, 16, 1
	v_add3_u32 v1, v1, v2, s7
	v_bfe_u32 v2, v0, 16, 1
	v_add3_u32 v0, v0, v2, s7
	ds_write_b16_d16_hi v142, v1 offset:13872
	ds_write_b16_d16_hi v142, v0 offset:13904
	v_and_b32_e32 v1, 0xffff0000, v1
	v_and_b32_e32 v0, 0xffff0000, v0
	v_add_f32_e32 v0, v1, v0
	v_mov_b32_e32 v1, 0
	s_nop 0
	v_add_f32_dpp v0, v0, v0 row_ror:8 row_mask:0xf bank_mask:0xf bound_ctrl:1
	s_nop 1
	v_add_f32_dpp v0, v0, v0 row_ror:4 row_mask:0xf bank_mask:0xf bound_ctrl:1
	s_nop 1
	v_add_f32_dpp v0, v0, v0 row_ror:2 row_mask:0xf bank_mask:0xf bound_ctrl:1
	s_nop 1
	v_mov_b32_dpp v1, v0 row_ror:1 row_mask:0xf bank_mask:0xf
	s_and_saveexec_b64 s[4:5], s[26:27]
	v_add_f32_e32 v0, v0, v1
	ds_write_b32 v143, v0 offset:204
	s_or_b64 exec, exec, s[4:5]
	v_mov_b32_e32 v0, 0
	s_mov_b32 s4, 0
	v_mov_b32_e32 v1, v144
	s_waitcnt lgkmcnt(0)
	s_barrier
	s_lshl_b32 s22, s50, 17
	v_add_co_u32_e32 v232, vcc, s22, v98
	s_nop 1
	v_addc_co_u32_e32 v233, vcc, 0, v99, vcc
	s_mov_b32 s22, 0x18042000
	v_add_co_u32_e32 v234, vcc, s22, v232
	s_nop 1
	v_addc_co_u32_e32 v235, vcc, 0, v233, vcc
	s_mov_b32 s22, 0x18044000
	v_add_co_u32_e32 v232, vcc, s22, v232
	s_nop 1
	v_addc_co_u32_e32 v233, vcc, 0, v233, vcc
	global_load_dwordx4 v[164:167], v[234:235], off
	global_load_dwordx4 v[196:199], v[232:233], off
	global_load_dwordx4 v[168:171], v[234:235], off offset:64
	global_load_dwordx4 v[200:203], v[232:233], off offset:64
	global_load_dwordx4 v[172:175], v[234:235], off offset:128
	global_load_dwordx4 v[204:207], v[232:233], off offset:128
	global_load_dwordx4 v[176:179], v[234:235], off offset:192
	global_load_dwordx4 v[208:211], v[232:233], off offset:192
	global_load_dwordx4 v[180:183], v[234:235], off offset:256
	global_load_dwordx4 v[216:219], v[232:233], off offset:256
	global_load_dwordx4 v[184:187], v[234:235], off offset:320
	global_load_dwordx4 v[220:223], v[232:233], off offset:320
	global_load_dwordx4 v[188:191], v[234:235], off offset:384
	global_load_dwordx4 v[224:227], v[232:233], off offset:384
	global_load_dwordx4 v[192:195], v[234:235], off offset:448
	global_load_dwordx4 v[228:231], v[232:233], off offset:448

; __device__ __forceinline__ f32x4 mfma16(bf16x8 a, bf16x8 b, f32x4 c) { return __builtin_amdgcn_mfma_f32_16x16x32_bf16(a, b, c, 0, 0, 0); }
; __device__ __forceinline__ void mlstm_out(const Params& P, unsigned char* shm, int bh, int j) {
;     ...
; #pragma unroll 2
;         for (int ks = 0; ks < 8; ++ks) { const bf16x8 cf0 = *(const bf16x8*)(cbase + 32 * ks), cf1 = *(const bf16x8*)(cbase + 16 * 256 + 32 * ks);
; #pragma unroll
;             for (int m = 0; m < 8; ++m) { const bf16x8 a = *(const bf16x8*)(qbase + 16 * m * 264 + 32 * ks);
;                 acc[m][0] = mfma16(a, cf0, acc[m][0]); acc[m][1] = mfma16(a, cf1, acc[m][1]); } }
.LBB0_591:
	s_nop 1
	ds_read_b128 v[28:31], v54
	s_waitcnt vmcnt(15) lgkmcnt(0)
	v_mfma_f32_16x16x32_bf16 v[0:3], v[28:31], v[164:167], v[0:3]
	s_waitcnt vmcnt(14)
	v_mfma_f32_16x16x32_bf16 v[4:7], v[28:31], v[196:199], v[4:7]
	ds_read_b128 v[28:31], v54 offset:8448
	s_waitcnt lgkmcnt(0)
	v_mfma_f32_16x16x32_bf16 v[8:11], v[28:31], v[164:167], v[8:11]
	v_mfma_f32_16x16x32_bf16 v[12:15], v[28:31], v[196:199], v[12:15]
	ds_read_b128 v[28:31], v54 offset:16896
	s_waitcnt lgkmcnt(0)
	v_mfma_f32_16x16x32_bf16 v[16:19], v[28:31], v[164:167], v[16:19]
	v_mfma_f32_16x16x32_bf16 v[32:35], v[28:31], v[196:199], v[32:35]
	ds_read_b128 v[28:31], v54 offset:25344
	s_waitcnt lgkmcnt(0)
	v_mfma_f32_16x16x32_bf16 v[36:39], v[28:31], v[164:167], v[36:39]
	v_mfma_f32_16x16x32_bf16 v[40:43], v[28:31], v[196:199], v[40:43]
	ds_read_b128 v[28:31], v54 offset:33792
	s_waitcnt lgkmcnt(0)
	v_mfma_f32_16x16x32_bf16 v[44:47], v[28:31], v[164:167], v[44:47]
	v_mfma_f32_16x16x32_bf16 v[56:59], v[28:31], v[196:199], v[64:67]
	ds_read_b128 v[28:31], v54 offset:42240
	s_waitcnt lgkmcnt(0)
	v_mfma_f32_16x16x32_bf16 v[60:63], v[28:31], v[164:167], v[68:71]
	v_mfma_f32_16x16x32_bf16 v[72:75], v[28:31], v[196:199], v[72:75]
	ds_read_b128 v[28:31], v54 offset:50688
	s_waitcnt lgkmcnt(0)
	v_mfma_f32_16x16x32_bf16 v[76:79], v[28:31], v[164:167], v[76:79]
	v_mfma_f32_16x16x32_bf16 v[80:83], v[28:31], v[196:199], v[80:83]
	ds_read_b128 v[28:31], v54 offset:59136
	s_waitcnt lgkmcnt(0)
	v_mfma_f32_16x16x32_bf16 v[20:23], v[28:31], v[164:167], v[84:87]
	v_mfma_f32_16x16x32_bf16 v[24:27], v[28:31], v[196:199], v[88:91]
	s_nop 0
	ds_read_b128 v[64:67], v54 offset:64
	s_waitcnt vmcnt(13) lgkmcnt(0)
	v_mfma_f32_16x16x32_bf16 v[0:3], v[64:67], v[168:171], v[0:3]
	s_waitcnt vmcnt(12)
	v_mfma_f32_16x16x32_bf16 v[4:7], v[64:67], v[200:203], v[4:7]
	ds_read_b128 v[64:67], v54 offset:8512
	s_waitcnt lgkmcnt(0)
	v_mfma_f32_16x16x32_bf16 v[8:11], v[64:67], v[168:171], v[8:11]
	v_mfma_f32_16x16x32_bf16 v[12:15], v[64:67], v[200:203], v[12:15]
	ds_read_b128 v[64:67], v54 offset:16960
	s_waitcnt lgkmcnt(0)
	v_mfma_f32_16x16x32_bf16 v[16:19], v[64:67], v[168:171], v[16:19]
	v_mfma_f32_16x16x32_bf16 v[32:35], v[64:67], v[200:203], v[32:35]
	ds_read_b128 v[64:67], v54 offset:25408
	s_waitcnt lgkmcnt(0)
	v_mfma_f32_16x16x32_bf16 v[36:39], v[64:67], v[168:171], v[36:39]
	v_mfma_f32_16x16x32_bf16 v[40:43], v[64:67], v[200:203], v[40:43]
	ds_read_b128 v[64:67], v54 offset:33856
	s_waitcnt lgkmcnt(0)
	v_mfma_f32_16x16x32_bf16 v[44:47], v[64:67], v[168:171], v[44:47]
	v_mfma_f32_16x16x32_bf16 v[64:67], v[64:67], v[200:203], v[56:59]
	s_nop 2
	ds_read_b128 v[56:59], v54 offset:42304
	s_waitcnt lgkmcnt(0)
	v_mfma_f32_16x16x32_bf16 v[68:71], v[56:59], v[168:171], v[60:63]
	v_mfma_f32_16x16x32_bf16 v[72:75], v[56:59], v[200:203], v[72:75]
	ds_read_b128 v[56:59], v54 offset:50752
	s_waitcnt lgkmcnt(0)
	v_mfma_f32_16x16x32_bf16 v[76:79], v[56:59], v[168:171], v[76:79]
	v_mfma_f32_16x16x32_bf16 v[80:83], v[56:59], v[200:203], v[80:83]
	ds_read_b128 v[56:59], v54 offset:59200
	v_add_u32_e32 v54, 0x80, v54
	s_waitcnt lgkmcnt(0)
	v_mfma_f32_16x16x32_bf16 v[84:87], v[56:59], v[168:171], v[20:23]
	v_mfma_f32_16x16x32_bf16 v[88:91], v[56:59], v[200:203], v[24:27]
	ds_read_b128 v[28:31], v54
	s_waitcnt vmcnt(11) lgkmcnt(0)
	v_mfma_f32_16x16x32_bf16 v[0:3], v[28:31], v[172:175], v[0:3]
	s_waitcnt vmcnt(10)
	v_mfma_f32_16x16x32_bf16 v[4:7], v[28:31], v[204:207], v[4:7]
	ds_read_b128 v[28:31], v54 offset:8448
	s_waitcnt lgkmcnt(0)
	v_mfma_f32_16x16x32_bf16 v[8:11], v[28:31], v[172:175], v[8:11]
	v_mfma_f32_16x16x32_bf16 v[12:15], v[28:31], v[204:207], v[12:15]
	ds_read_b128 v[28:31], v54 offset:16896
	s_waitcnt lgkmcnt(0)
	v_mfma_f32_16x16x32_bf16 v[16:19], v[28:31], v[172:175], v[16:19]
	v_mfma_f32_16x16x32_bf16 v[32:35], v[28:31], v[204:207], v[32:35]
	ds_read_b128 v[28:31], v54 offset:25344
	s_waitcnt lgkmcnt(0)
	v_mfma_f32_16x16x32_bf16 v[36:39], v[28:31], v[172:175], v[36:39]
	v_mfma_f32_16x16x32_bf16 v[40:43], v[28:31], v[204:207], v[40:43]
	ds_read_b128 v[28:31], v54 offset:33792
	s_waitcnt lgkmcnt(0)
	v_mfma_f32_16x16x32_bf16 v[44:47], v[28:31], v[172:175], v[44:47]
	v_mfma_f32_16x16x32_bf16 v[56:59], v[28:31], v[204:207], v[64:67]
	ds_read_b128 v[28:31], v54 offset:42240
	s_waitcnt lgkmcnt(0)
	v_mfma_f32_16x16x32_bf16 v[60:63], v[28:31], v[172:175], v[68:71]
	v_mfma_f32_16x16x32_bf16 v[72:75], v[28:31], v[204:207], v[72:75]
	ds_read_b128 v[28:31], v54 offset:50688
	s_waitcnt lgkmcnt(0)
	v_mfma_f32_16x16x32_bf16 v[76:79], v[28:31], v[172:175], v[76:79]
	v_mfma_f32_16x16x32_bf16 v[80:83], v[28:31], v[204:207], v[80:83]
	ds_read_b128 v[28:31], v54 offset:59136
	s_waitcnt lgkmcnt(0)
	v_mfma_f32_16x16x32_bf16 v[20:23], v[28:31], v[172:175], v[84:87]
	v_mfma_f32_16x16x32_bf16 v[24:27], v[28:31], v[204:207], v[88:91]
	s_nop 0
	ds_read_b128 v[64:67], v54 offset:64
	s_waitcnt vmcnt(9) lgkmcnt(0)
	v_mfma_f32_16x16x32_bf16 v[0:3], v[64:67], v[176:179], v[0:3]
	s_waitcnt vmcnt(8)
	v_mfma_f32_16x16x32_bf16 v[4:7], v[64:67], v[208:211], v[4:7]
	ds_read_b128 v[64:67], v54 offset:8512
	s_waitcnt lgkmcnt(0)
	v_mfma_f32_16x16x32_bf16 v[8:11], v[64:67], v[176:179], v[8:11]
	v_mfma_f32_16x16x32_bf16 v[12:15], v[64:67], v[208:211], v[12:15]
	ds_read_b128 v[64:67], v54 offset:16960
	s_waitcnt lgkmcnt(0)
	v_mfma_f32_16x16x32_bf16 v[16:19], v[64:67], v[176:179], v[16:19]
	v_mfma_f32_16x16x32_bf16 v[32:35], v[64:67], v[208:211], v[32:35]
	ds_read_b128 v[64:67], v54 offset:25408
	s_waitcnt lgkmcnt(0)
	v_mfma_f32_16x16x32_bf16 v[36:39], v[64:67], v[176:179], v[36:39]
	v_mfma_f32_16x16x32_bf16 v[40:43], v[64:67], v[208:211], v[40:43]
	ds_read_b128 v[64:67], v54 offset:33856
	s_waitcnt lgkmcnt(0)
; __device__ __forceinline__ f32x4 mfma16(bf16x8 a, bf16x8 b, f32x4 c) { return __builtin_amdgcn_mfma_f32_16x16x32_bf16(a, b, c, 0, 0, 0); }
; __device__ __forceinline__ void mlstm_out(const Params& P, unsigned char* shm, int bh, int j) {
;     ...
; #pragma unroll 2
;         for (int ks = 0; ks < 8; ++ks) { const bf16x8 cf0 = *(const bf16x8*)(cbase + 32 * ks), cf1 = *(const bf16x8*)(cbase + 16 * 256 + 32 * ks);
; #pragma unroll
;             for (int m = 0; m < 8; ++m) { const bf16x8 a = *(const bf16x8*)(qbase + 16 * m * 264 + 32 * ks);
;                 acc[m][0] = mfma16(a, cf0, acc[m][0]); acc[m][1] = mfma16(a, cf1, acc[m][1]); } }
	v_mfma_f32_16x16x32_bf16 v[44:47], v[64:67], v[176:179], v[44:47]
	v_mfma_f32_16x16x32_bf16 v[64:67], v[64:67], v[208:211], v[56:59]
	s_nop 2
	ds_read_b128 v[56:59], v54 offset:42304
	s_waitcnt lgkmcnt(0)
	v_mfma_f32_16x16x32_bf16 v[68:71], v[56:59], v[176:179], v[60:63]
	v_mfma_f32_16x16x32_bf16 v[72:75], v[56:59], v[208:211], v[72:75]
	ds_read_b128 v[56:59], v54 offset:50752
	s_waitcnt lgkmcnt(0)
	v_mfma_f32_16x16x32_bf16 v[76:79], v[56:59], v[176:179], v[76:79]
	v_mfma_f32_16x16x32_bf16 v[80:83], v[56:59], v[208:211], v[80:83]
	ds_read_b128 v[56:59], v54 offset:59200
	v_add_u32_e32 v54, 0x80, v54
	s_waitcnt lgkmcnt(0)
	v_mfma_f32_16x16x32_bf16 v[84:87], v[56:59], v[176:179], v[20:23]
	v_mfma_f32_16x16x32_bf16 v[88:91], v[56:59], v[208:211], v[24:27]
	ds_read_b128 v[28:31], v54
	s_waitcnt vmcnt(7) lgkmcnt(0)
	v_mfma_f32_16x16x32_bf16 v[0:3], v[28:31], v[180:183], v[0:3]
	s_waitcnt vmcnt(6)
	v_mfma_f32_16x16x32_bf16 v[4:7], v[28:31], v[216:219], v[4:7]
	ds_read_b128 v[28:31], v54 offset:8448
	s_waitcnt lgkmcnt(0)
	v_mfma_f32_16x16x32_bf16 v[8:11], v[28:31], v[180:183], v[8:11]
	v_mfma_f32_16x16x32_bf16 v[12:15], v[28:31], v[216:219], v[12:15]
	ds_read_b128 v[28:31], v54 offset:16896
	s_waitcnt lgkmcnt(0)
	v_mfma_f32_16x16x32_bf16 v[16:19], v[28:31], v[180:183], v[16:19]
	v_mfma_f32_16x16x32_bf16 v[32:35], v[28:31], v[216:219], v[32:35]
	ds_read_b128 v[28:31], v54 offset:25344
	s_waitcnt lgkmcnt(0)
	v_mfma_f32_16x16x32_bf16 v[36:39], v[28:31], v[180:183], v[36:39]
	v_mfma_f32_16x16x32_bf16 v[40:43], v[28:31], v[216:219], v[40:43]
	ds_read_b128 v[28:31], v54 offset:33792
	s_waitcnt lgkmcnt(0)
	v_mfma_f32_16x16x32_bf16 v[44:47], v[28:31], v[180:183], v[44:47]
	v_mfma_f32_16x16x32_bf16 v[56:59], v[28:31], v[216:219], v[64:67]
	ds_read_b128 v[28:31], v54 offset:42240
	s_waitcnt lgkmcnt(0)
	v_mfma_f32_16x16x32_bf16 v[60:63], v[28:31], v[180:183], v[68:71]
	v_mfma_f32_16x16x32_bf16 v[72:75], v[28:31], v[216:219], v[72:75]
	ds_read_b128 v[28:31], v54 offset:50688
	s_waitcnt lgkmcnt(0)
	v_mfma_f32_16x16x32_bf16 v[76:79], v[28:31], v[180:183], v[76:79]
	v_mfma_f32_16x16x32_bf16 v[80:83], v[28:31], v[216:219], v[80:83]
	ds_read_b128 v[28:31], v54 offset:59136
	s_waitcnt lgkmcnt(0)
	v_mfma_f32_16x16x32_bf16 v[20:23], v[28:31], v[180:183], v[84:87]
	v_mfma_f32_16x16x32_bf16 v[24:27], v[28:31], v[216:219], v[88:91]
	s_nop 0
	ds_read_b128 v[64:67], v54 offset:64
	s_waitcnt vmcnt(5) lgkmcnt(0)
	v_mfma_f32_16x16x32_bf16 v[0:3], v[64:67], v[184:187], v[0:3]
	s_waitcnt vmcnt(4)
	v_mfma_f32_16x16x32_bf16 v[4:7], v[64:67], v[220:223], v[4:7]
	ds_read_b128 v[64:67], v54 offset:8512
	s_waitcnt lgkmcnt(0)
	v_mfma_f32_16x16x32_bf16 v[8:11], v[64:67], v[184:187], v[8:11]
	v_mfma_f32_16x16x32_bf16 v[12:15], v[64:67], v[220:223], v[12:15]
	ds_read_b128 v[64:67], v54 offset:16960
	s_waitcnt lgkmcnt(0)
	v_mfma_f32_16x16x32_bf16 v[16:19], v[64:67], v[184:187], v[16:19]
	v_mfma_f32_16x16x32_bf16 v[32:35], v[64:67], v[220:223], v[32:35]
	ds_read_b128 v[64:67], v54 offset:25408
	s_waitcnt lgkmcnt(0)
	v_mfma_f32_16x16x32_bf16 v[36:39], v[64:67], v[184:187], v[36:39]
	v_mfma_f32_16x16x32_bf16 v[40:43], v[64:67], v[220:223], v[40:43]
	ds_read_b128 v[64:67], v54 offset:33856
	s_waitcnt lgkmcnt(0)
	v_mfma_f32_16x16x32_bf16 v[44:47], v[64:67], v[184:187], v[44:47]
	v_mfma_f32_16x16x32_bf16 v[64:67], v[64:67], v[220:223], v[56:59]
	s_nop 2
	ds_read_b128 v[56:59], v54 offset:42304
	s_waitcnt lgkmcnt(0)
	v_mfma_f32_16x16x32_bf16 v[68:71], v[56:59], v[184:187], v[60:63]
	v_mfma_f32_16x16x32_bf16 v[72:75], v[56:59], v[220:223], v[72:75]
	ds_read_b128 v[56:59], v54 offset:50752
	s_waitcnt lgkmcnt(0)
	v_mfma_f32_16x16x32_bf16 v[76:79], v[56:59], v[184:187], v[76:79]
	v_mfma_f32_16x16x32_bf16 v[80:83], v[56:59], v[220:223], v[80:83]
	ds_read_b128 v[56:59], v54 offset:59200
	v_add_u32_e32 v54, 0x80, v54
	s_waitcnt lgkmcnt(0)
	v_mfma_f32_16x16x32_bf16 v[84:87], v[56:59], v[184:187], v[20:23]
	v_mfma_f32_16x16x32_bf16 v[88:91], v[56:59], v[220:223], v[24:27]
	ds_read_b128 v[28:31], v54
	s_waitcnt vmcnt(3) lgkmcnt(0)
	v_mfma_f32_16x16x32_bf16 v[0:3], v[28:31], v[188:191], v[0:3]
	s_waitcnt vmcnt(2)
	v_mfma_f32_16x16x32_bf16 v[4:7], v[28:31], v[224:227], v[4:7]
	ds_read_b128 v[28:31], v54 offset:8448
	s_waitcnt lgkmcnt(0)
	v_mfma_f32_16x16x32_bf16 v[8:11], v[28:31], v[188:191], v[8:11]
	v_mfma_f32_16x16x32_bf16 v[12:15], v[28:31], v[224:227], v[12:15]
	ds_read_b128 v[28:31], v54 offset:16896
	s_waitcnt lgkmcnt(0)
	v_mfma_f32_16x16x32_bf16 v[16:19], v[28:31], v[188:191], v[16:19]
	v_mfma_f32_16x16x32_bf16 v[32:35], v[28:31], v[224:227], v[32:35]
	ds_read_b128 v[28:31], v54 offset:25344
	s_waitcnt lgkmcnt(0)
	v_mfma_f32_16x16x32_bf16 v[36:39], v[28:31], v[188:191], v[36:39]
	v_mfma_f32_16x16x32_bf16 v[40:43], v[28:31], v[224:227], v[40:43]
	ds_read_b128 v[28:31], v54 offset:33792
	s_waitcnt lgkmcnt(0)
	v_mfma_f32_16x16x32_bf16 v[44:47], v[28:31], v[188:191], v[44:47]
	v_mfma_f32_16x16x32_bf16 v[56:59], v[28:31], v[224:227], v[64:67]
	ds_read_b128 v[28:31], v54 offset:42240
	s_waitcnt lgkmcnt(0)
	v_mfma_f32_16x16x32_bf16 v[60:63], v[28:31], v[188:191], v[68:71]
	v_mfma_f32_16x16x32_bf16 v[72:75], v[28:31], v[224:227], v[72:75]
	ds_read_b128 v[28:31], v54 offset:50688
	s_waitcnt lgkmcnt(0)
	v_mfma_f32_16x16x32_bf16 v[76:79], v[28:31], v[188:191], v[76:79]
	v_mfma_f32_16x16x32_bf16 v[80:83], v[28:31], v[224:227], v[80:83]
	ds_read_b128 v[28:31], v54 offset:59136
	s_waitcnt lgkmcnt(0)
	v_mfma_f32_16x16x32_bf16 v[20:23], v[28:31], v[188:191], v[84:87]
	v_mfma_f32_16x16x32_bf16 v[24:27], v[28:31], v[224:227], v[88:91]
	s_nop 0
	ds_read_b128 v[64:67], v54 offset:64
	s_waitcnt vmcnt(1) lgkmcnt(0)
; __device__ __forceinline__ f32x4 mfma16(bf16x8 a, bf16x8 b, f32x4 c) { return __builtin_amdgcn_mfma_f32_16x16x32_bf16(a, b, c, 0, 0, 0); }
; #define MFMA_SETTLE() do { __builtin_amdgcn_sched_barrier(0); asm volatile("s_nop 15\n\ts_nop 15" ::: "memory"); __builtin_amdgcn_sched_barrier(0); } while (0)
; __device__ __forceinline__ void mlstm_out(const Params& P, unsigned char* shm, int bh, int j) {
;     ...
;     {
;         const bf16_t* cbase = (const bf16_t*)(P.ws + O_CTB) + (size_t)(bh * 16 + j - 1) * 65536 + (32 * wave + l16) * 256 + 8 * q;
;         const bf16_t* qbase = Qs + l16 * 264 + 8 * q;
; #pragma unroll 2
;         for (int ks = 0; ks < 8; ++ks) { const bf16x8 cf0 = *(const bf16x8*)(cbase + 32 * ks), cf1 = *(const bf16x8*)(cbase + 16 * 256 + 32 * ks);
; #pragma unroll
;             for (int m = 0; m < 8; ++m) { const bf16x8 a = *(const bf16x8*)(qbase + 16 * m * 264 + 32 * ks);
;                 acc[m][0] = mfma16(a, cf0, acc[m][0]); acc[m][1] = mfma16(a, cf1, acc[m][1]); } }
;         MFMA_SETTLE();
;         const float* pWi = sWi + 4 * q;
; #pragma unroll
;         for (int m = 0; m < 8; ++m)
; #pragma unroll
;             for (int r = 0; r < 4; ++r) { const float w = pWi[16 * m + r]; acc[m][0][r] *= w; acc[m][1][r] *= w; }
;     }
;     unsigned opk[8][4];
;     { const bf16_t* obase = PR + (4 * q) * NPROJ + C_O + 32 * wave + l16;
; #pragma unroll
;       for (int m = 0; m < 8; ++m)
; #pragma unroll
;           for (int r = 0; r < 4; ++r) opk[m][r] = (unsigned)obase[(16 * m + r) * NPROJ] | ((unsigned)obase[(16 * m + r) * NPROJ + 16] << 16); }
	v_mfma_f32_16x16x32_bf16 v[0:3], v[64:67], v[192:195], v[0:3]
	s_waitcnt vmcnt(0)
	v_mfma_f32_16x16x32_bf16 v[4:7], v[64:67], v[228:231], v[4:7]
	ds_read_b128 v[64:67], v54 offset:8512
	s_waitcnt lgkmcnt(0)
	v_mfma_f32_16x16x32_bf16 v[8:11], v[64:67], v[192:195], v[8:11]
	v_mfma_f32_16x16x32_bf16 v[12:15], v[64:67], v[228:231], v[12:15]
	ds_read_b128 v[64:67], v54 offset:16960
	s_waitcnt lgkmcnt(0)
	v_mfma_f32_16x16x32_bf16 v[16:19], v[64:67], v[192:195], v[16:19]
	v_mfma_f32_16x16x32_bf16 v[32:35], v[64:67], v[228:231], v[32:35]
	ds_read_b128 v[64:67], v54 offset:25408
	s_waitcnt lgkmcnt(0)
	v_mfma_f32_16x16x32_bf16 v[36:39], v[64:67], v[192:195], v[36:39]
	v_mfma_f32_16x16x32_bf16 v[40:43], v[64:67], v[228:231], v[40:43]
	ds_read_b128 v[64:67], v54 offset:33856
	s_waitcnt lgkmcnt(0)
	v_mfma_f32_16x16x32_bf16 v[44:47], v[64:67], v[192:195], v[44:47]
	v_mfma_f32_16x16x32_bf16 v[64:67], v[64:67], v[228:231], v[56:59]
	s_nop 2
	ds_read_b128 v[56:59], v54 offset:42304
	s_waitcnt lgkmcnt(0)
	v_mfma_f32_16x16x32_bf16 v[68:71], v[56:59], v[192:195], v[60:63]
	v_mfma_f32_16x16x32_bf16 v[72:75], v[56:59], v[228:231], v[72:75]
	ds_read_b128 v[56:59], v54 offset:50752
	s_waitcnt lgkmcnt(0)
	v_mfma_f32_16x16x32_bf16 v[76:79], v[56:59], v[192:195], v[76:79]
	v_mfma_f32_16x16x32_bf16 v[80:83], v[56:59], v[228:231], v[80:83]
	ds_read_b128 v[56:59], v54 offset:59200
	v_add_u32_e32 v54, 0x80, v54
	s_waitcnt lgkmcnt(0)
	v_mfma_f32_16x16x32_bf16 v[84:87], v[56:59], v[192:195], v[20:23]
	v_mfma_f32_16x16x32_bf16 v[88:91], v[56:59], v[228:231], v[24:27]
	s_lshl_b32 s4, s48, 7
	s_nop 15
	s_nop 15
	ds_read_b128 v[20:23], v151
	v_mov_b32_e32 v109, v97
	v_mov_b32_e32 v111, v97
	v_mov_b32_e32 v113, v97
	s_movk_i32 s5, 0x2000
	s_waitcnt lgkmcnt(0)
	v_pk_mul_f32 v[30:31], v[2:3], v[22:23]
	v_pk_mul_f32 v[28:29], v[0:1], v[20:21]
	ds_read_b128 v[0:3], v151 offset:64
	v_pk_mul_f32 v[62:63], v[6:7], v[22:23]
	v_pk_mul_f32 v[60:61], v[4:5], v[20:21]
	s_mov_b64 s[22:23], 0x2000
	s_add_i32 s4, s69, s4
	s_waitcnt lgkmcnt(0)
	v_pk_mul_f32 v[26:27], v[10:11], v[2:3]
	v_pk_mul_f32 v[24:25], v[8:9], v[0:1]
	v_pk_mul_f32 v[58:59], v[14:15], v[2:3]
	v_pk_mul_f32 v[56:57], v[12:13], v[0:1]
	ds_read_b128 v[0:3], v151 offset:128
	v_mov_b32_e32 v190, v160
	s_waitcnt lgkmcnt(0)
	v_pk_mul_f32 v[22:23], v[18:19], v[2:3]
	v_pk_mul_f32 v[20:21], v[16:17], v[0:1]
	v_pk_mul_f32 v[54:55], v[34:35], v[2:3]
	v_pk_mul_f32 v[52:53], v[32:33], v[0:1]
	ds_read_b128 v[0:3], v151 offset:192
	ds_read_b128 v[32:35], v151 offset:448
	s_waitcnt lgkmcnt(1)
	v_pk_mul_f32 v[18:19], v[38:39], v[2:3]
	v_pk_mul_f32 v[16:17], v[36:37], v[0:1]
	v_pk_mul_f32 v[50:51], v[42:43], v[2:3]
	v_pk_mul_f32 v[48:49], v[40:41], v[0:1]
	ds_read_b128 v[0:3], v151 offset:256
	s_waitcnt lgkmcnt(0)
	v_pk_mul_f32 v[14:15], v[46:47], v[2:3]
	v_pk_mul_f32 v[12:13], v[44:45], v[0:1]
	v_pk_mul_f32 v[46:47], v[66:67], v[2:3]
	v_pk_mul_f32 v[44:45], v[64:65], v[0:1]
	ds_read_b128 v[0:3], v151 offset:320
	v_lshl_add_u64 v[64:65], s[44:45], 0, v[108:109]
	v_lshl_add_u64 v[64:65], v[64:65], 0, v[110:111]
	v_lshl_add_u64 v[64:65], v[64:65], 0, v[112:113]
	v_lshl_add_u64 v[66:67], v[64:65], 0, s[22:23]
	s_waitcnt lgkmcnt(0)
	v_pk_mul_f32 v[8:9], v[68:69], v[0:1]
	v_add_co_u32_e32 v68, vcc, s5, v64
	s_movk_i32 s5, 0x6000
	s_nop 0
	v_addc_co_u32_e32 v69, vcc, 0, v65, vcc
	v_pk_mul_f32 v[10:11], v[70:71], v[2:3]
	v_pk_mul_f32 v[42:43], v[74:75], v[2:3]
	v_pk_mul_f32 v[40:41], v[72:73], v[0:1]
	ds_read_b128 v[0:3], v151 offset:384
	global_load_ushort v119, v[68:69], off
	global_load_ushort v120, v[66:67], off offset:32
	v_add_co_u32_e32 v66, vcc, s5, v64
	s_mov_b32 s5, 0xb000
	s_nop 0
	v_addc_co_u32_e32 v67, vcc, 0, v65, vcc
	global_load_ushort v118, v[66:67], off offset:2048
	global_load_ushort v121, v[66:67], off offset:2080
	v_add_co_u32_e32 v66, vcc, s5, v64
	s_mov_b32 s5, 0xf000
	s_nop 0
	v_addc_co_u32_e32 v67, vcc, 0, v65, vcc
	global_load_ushort v116, v[66:67], off
	global_load_ushort v122, v[66:67], off offset:32
	v_add_co_u32_e32 v66, vcc, s5, v64
	s_mov_b32 s5, 0x4a000
	s_nop 0
	v_addc_co_u32_e32 v67, vcc, 0, v65, vcc
	global_load_ushort v117, v[66:67], off offset:2048
	global_load_ushort v123, v[66:67], off offset:2080
	v_add_co_u32_e32 v66, vcc, s5, v64
	s_mov_b32 s5, 0x4e000
	s_nop 0
	v_addc_co_u32_e32 v67, vcc, 0, v65, vcc
	global_load_ushort v113, v[66:67], off
	global_load_ushort v124, v[66:67], off offset:32
	v_add_co_u32_e32 v66, vcc, s5, v64
	s_mov_b32 s5, 0x53000
	s_nop 0
	v_addc_co_u32_e32 v67, vcc, 0, v65, vcc
	global_load_ushort v111, v[66:67], off offset:2048
	global_load_ushort v125, v[66:67], off offset:2080
	v_add_co_u32_e32 v66, vcc, s5, v64
	s_mov_b32 s5, 0x57000
	s_nop 0
	v_addc_co_u32_e32 v67, vcc, 0, v65, vcc
	global_load_ushort v109, v[66:67], off
	global_load_ushort v126, v[66:67], off offset:32
	v_add_co_u32_e32 v66, vcc, s5, v64
	s_mov_b32 s5, 0x92000
	s_nop 0
	v_addc_co_u32_e32 v67, vcc, 0, v65, vcc
	global_load_ushort v107, v[66:67], off offset:2048
	global_load_ushort v127, v[66:67], off offset:2080
	v_add_co_u32_e32 v66, vcc, s5, v64
	s_mov_b32 s5, 0x96000
	s_nop 0
	v_addc_co_u32_e32 v67, vcc, 0, v65, vcc
	global_load_ushort v105, v[66:67], off
	global_load_ushort v128, v[66:67], off offset:32
	v_add_co_u32_e32 v66, vcc, s5, v64
	s_mov_b32 s5, 0x9b000
	s_nop 0
	v_addc_co_u32_e32 v67, vcc, 0, v65, vcc
	global_load_ushort v95, v[66:67], off offset:2048
	global_load_ushort v129, v[66:67], off offset:2080
	v_add_co_u32_e32 v66, vcc, s5, v64
	s_mov_b32 s5, 0x9f000
	s_nop 0
	v_addc_co_u32_e32 v67, vcc, 0, v65, vcc
	global_load_ushort v94, v[66:67], off
	global_load_ushort v168, v[66:67], off offset:32
	v_add_co_u32_e32 v66, vcc, s5, v64
	s_mov_b32 s5, 0xda000
	s_nop 0
	v_addc_co_u32_e32 v67, vcc, 0, v65, vcc
	global_load_ushort v103, v[66:67], off offset:2048
	global_load_ushort v169, v[66:67], off offset:2080
	v_add_co_u32_e32 v66, vcc, s5, v64
	s_mov_b32 s5, 0xde000
	s_nop 0
	v_addc_co_u32_e32 v67, vcc, 0, v65, vcc
	global_load_ushort v93, v[66:67], off
	global_load_ushort v170, v[66:67], off offset:32
	v_add_co_u32_e32 v66, vcc, s5, v64
	s_mov_b32 s5, 0xe3000
	s_nop 0
	v_addc_co_u32_e32 v67, vcc, 0, v65, vcc
	global_load_ushort v92, v[66:67], off offset:2048
	global_load_ushort v171, v[66:67], off offset:2080
	v_add_co_u32_e32 v66, vcc, s5, v64
	s_mov_b32 s5, 0xe7000
	s_nop 0
	v_addc_co_u32_e32 v67, vcc, 0, v65, vcc
	s_waitcnt lgkmcnt(0)
; __device__ __forceinline__ void mlstm_out(const Params& P, unsigned char* shm, int bh, int j) {
;     ...
;         const float* pWi = sWi + 4 * q;
; #pragma unroll
;         for (int m = 0; m < 8; ++m)
; #pragma unroll
;             for (int r = 0; r < 4; ++r) { const float w = pWi[16 * m + r]; acc[m][0][r] *= w; acc[m][1][r] *= w; }
;     }
;     unsigned opk[8][4];
;     { const bf16_t* obase = PR + (4 * q) * NPROJ + C_O + 32 * wave + l16;
; #pragma unroll
;       for (int m = 0; m < 8; ++m)
; #pragma unroll
;           for (int r = 0; r < 4; ++r) opk[m][r] = (unsigned)obase[(16 * m + r) * NPROJ] | ((unsigned)obase[(16 * m + r) * NPROJ + 16] << 16); }
;     {
;         const bf16_t* sbase = Ss + l16 * 136 + 8 * q;
; #pragma unroll 1
;         for (int ks = 0; ks < 4; ++ks) { bf16x8 vf0, vf1;
;             const bf16_t* vp = PR + (32 * ks + 8 * q) * NPROJ + C_V + 32 * wave + l16;
	v_pk_mul_f32 v[6:7], v[78:79], v[2:3]
	v_pk_mul_f32 v[38:39], v[82:83], v[2:3]
	v_pk_mul_f32 v[2:3], v[86:87], v[34:35]
	v_pk_mul_f32 v[34:35], v[90:91], v[34:35]
	global_load_ushort v91, v[66:67], off
	global_load_ushort v172, v[66:67], off offset:32
	v_add_co_u32_e32 v66, vcc, s5, v64
	s_mov_b32 s5, 0x122000
	s_nop 0
	v_addc_co_u32_e32 v67, vcc, 0, v65, vcc
	global_load_ushort v90, v[66:67], off offset:2048
	global_load_ushort v173, v[66:67], off offset:2080
	v_add_co_u32_e32 v66, vcc, s5, v64
	s_mov_b32 s5, 0x126000
	s_nop 0
	v_addc_co_u32_e32 v67, vcc, 0, v65, vcc
	v_pk_mul_f32 v[4:5], v[76:77], v[0:1]
	v_pk_mul_f32 v[36:37], v[80:81], v[0:1]
	v_pk_mul_f32 v[0:1], v[84:85], v[32:33]
	v_pk_mul_f32 v[32:33], v[88:89], v[32:33]
	global_load_ushort v89, v[66:67], off
	global_load_ushort v174, v[66:67], off offset:32
	v_add_co_u32_e32 v66, vcc, s5, v64
	s_mov_b32 s5, 0x12b000
	s_nop 0
	v_addc_co_u32_e32 v67, vcc, 0, v65, vcc
	global_load_ushort v87, v[66:67], off offset:2048
	global_load_ushort v175, v[66:67], off offset:2080
	v_add_co_u32_e32 v66, vcc, s5, v64
	s_mov_b32 s5, 0x12f000
	s_nop 0
	v_addc_co_u32_e32 v67, vcc, 0, v65, vcc
	global_load_ushort v86, v[66:67], off
	global_load_ushort v176, v[66:67], off offset:32
	v_add_co_u32_e32 v66, vcc, s5, v64
	s_mov_b32 s5, 0x16a000
	s_nop 0
	v_addc_co_u32_e32 v67, vcc, 0, v65, vcc
	global_load_ushort v88, v[66:67], off offset:2048
	global_load_ushort v177, v[66:67], off offset:2080
	v_add_co_u32_e32 v66, vcc, s5, v64
	s_mov_b32 s5, 0x16e000
	s_nop 0
	v_addc_co_u32_e32 v67, vcc, 0, v65, vcc
	global_load_ushort v85, v[66:67], off
	global_load_ushort v178, v[66:67], off offset:32
	v_add_co_u32_e32 v66, vcc, s5, v64
	s_mov_b32 s5, 0x173000
	s_nop 0
	v_addc_co_u32_e32 v67, vcc, 0, v65, vcc
	global_load_ushort v84, v[66:67], off offset:2048
	global_load_ushort v179, v[66:67], off offset:2080
	v_add_co_u32_e32 v66, vcc, s5, v64
	s_mov_b32 s5, 0x177000
	s_nop 0
	v_addc_co_u32_e32 v67, vcc, 0, v65, vcc
	global_load_ushort v83, v[66:67], off
	global_load_ushort v180, v[66:67], off offset:32
	v_add_co_u32_e32 v66, vcc, s5, v64
	s_mov_b32 s5, 0x1b2000
	s_nop 0
	v_addc_co_u32_e32 v67, vcc, 0, v65, vcc
	global_load_ushort v82, v[66:67], off offset:2048
	global_load_ushort v181, v[66:67], off offset:2080
	v_add_co_u32_e32 v66, vcc, s5, v64
	s_mov_b32 s5, 0x1b6000
	s_nop 0
	v_addc_co_u32_e32 v67, vcc, 0, v65, vcc
	global_load_ushort v81, v[66:67], off
	global_load_ushort v182, v[66:67], off offset:32
	v_add_co_u32_e32 v66, vcc, s5, v64
	s_mov_b32 s5, 0x1bb000
	s_nop 0
	v_addc_co_u32_e32 v67, vcc, 0, v65, vcc
	global_load_ushort v79, v[66:67], off offset:2048
	global_load_ushort v183, v[66:67], off offset:2080
	v_add_co_u32_e32 v66, vcc, s5, v64
	s_mov_b32 s5, 0x1bf000
	s_nop 0
	v_addc_co_u32_e32 v67, vcc, 0, v65, vcc
	global_load_ushort v78, v[66:67], off
	global_load_ushort v184, v[66:67], off offset:32
	v_add_co_u32_e32 v66, vcc, s5, v64
	s_mov_b32 s5, 0x1fa000
	s_nop 0
	v_addc_co_u32_e32 v67, vcc, 0, v65, vcc
	global_load_ushort v80, v[66:67], off offset:2048
	global_load_ushort v185, v[66:67], off offset:2080
	v_add_co_u32_e32 v66, vcc, s5, v64
	s_mov_b32 s5, 0x1fe000
	s_nop 0
	v_addc_co_u32_e32 v67, vcc, 0, v65, vcc
	global_load_ushort v77, v[66:67], off
	global_load_ushort v186, v[66:67], off offset:32
	v_add_co_u32_e32 v66, vcc, s5, v64
	s_mov_b32 s5, 0x203000
	s_nop 0
	v_addc_co_u32_e32 v67, vcc, 0, v65, vcc
	global_load_ushort v76, v[66:67], off offset:2048
	global_load_ushort v187, v[66:67], off offset:2080
	v_add_co_u32_e32 v66, vcc, s5, v64
	s_lshl_b32 s22, s50, 5
	s_nop 0
	v_addc_co_u32_e32 v67, vcc, 0, v65, vcc
	v_add_co_u32_e32 v64, vcc, 0x207000, v64
	global_load_ushort v75, v[66:67], off
	global_load_ushort v188, v[66:67], off offset:32
	v_addc_co_u32_e32 v65, vcc, 0, v65, vcc
	global_load_ushort v74, v[64:65], off offset:2048
	global_load_ushort v189, v[64:65], off offset:2080
	s_mul_hi_i32 s5, s4, 0x4800
	s_mulk_i32 s4, 0x4800
	s_and_b32 s22, s22, 0x600
	s_or_b32 s4, s4, s22
	v_lshl_add_u64 v[72:73], v[100:101], 0, s[4:5]
	s_mov_b64 s[4:5], 0
